# attention bias-table builds: the 8 (neighbourhood item) / 3 (dilated pass) gather loads issued together with one wait instead of one round trip each
# speedup vs baseline: 1.0090x; 1.0090x over previous
.LBB0_146:
	s_cmpk_gt_i32 s83, 0xff
	s_mov_b64 s[0:1], -1
	s_cbranch_scc0 .LBB0_184
	s_and_b32 s3, s83, 7
	s_or_b32 s0, s3, s59
	s_mulk_i32 s0, 0x744
	s_add_u32 s0, s72, s0
	s_addc_u32 s1, s73, 0
	v_mov_b32_e32 v6, 0xf149f2ca
	v_mov_b32_e32 v7, 0xf149f2ca
	v_mov_b32_e32 v8, 0xf149f2ca
	v_mov_b32_e32 v9, 0xf149f2ca
	v_mov_b32_e32 v10, 0xf149f2ca
	v_mov_b32_e32 v11, 0xf149f2ca
	v_mov_b32_e32 v12, 0xf149f2ca
	v_mov_b32_e32 v13, 0xf149f2ca
	s_mov_b64 s[12:13], exec
	v_readlane_b32 s8, v252, 38
	v_readlane_b32 s9, v252, 39
	s_and_b64 s[8:9], s[12:13], s[8:9]
	s_mov_b64 exec, s[8:9]
	s_cbranch_execz .Lnbtbl_ld0
	v_lshl_add_u64 v[2:3], v[148:149], 2, s[0:1]
	global_load_dword v6, v[2:3], off
.Lnbtbl_ld0:
	s_or_b64 exec, exec, s[12:13]
	s_mov_b64 s[12:13], exec
	v_readlane_b32 s8, v252, 41
	v_readlane_b32 s9, v252, 42
	s_and_b64 s[8:9], s[12:13], s[8:9]
	s_mov_b64 exec, s[8:9]
	s_cbranch_execz .Lnbtbl_ld1
	v_lshl_add_u64 v[2:3], v[150:151], 2, s[0:1]
	global_load_dword v7, v[2:3], off
.Lnbtbl_ld1:
	s_or_b64 exec, exec, s[12:13]
	s_mov_b64 s[12:13], exec
	v_readlane_b32 s8, v252, 43
	v_readlane_b32 s9, v252, 44
	s_and_b64 s[8:9], s[12:13], s[8:9]
	s_mov_b64 exec, s[8:9]
	s_cbranch_execz .Lnbtbl_ld2
	v_lshl_add_u64 v[2:3], v[152:153], 2, s[0:1]
	global_load_dword v8, v[2:3], off
.Lnbtbl_ld2:
	s_or_b64 exec, exec, s[12:13]
	s_mov_b64 s[12:13], exec
	v_readlane_b32 s8, v252, 45
	v_readlane_b32 s9, v252, 46
	s_and_b64 s[8:9], s[12:13], s[8:9]
	s_mov_b64 exec, s[8:9]
	s_cbranch_execz .Lnbtbl_ld3
	v_lshl_add_u64 v[2:3], v[154:155], 2, s[0:1]
	global_load_dword v9, v[2:3], off
.Lnbtbl_ld3:
	s_or_b64 exec, exec, s[12:13]
	s_mov_b64 s[12:13], exec
	v_readlane_b32 s8, v252, 47
	v_readlane_b32 s9, v252, 48
	s_and_b64 s[8:9], s[12:13], s[8:9]
	s_mov_b64 exec, s[8:9]
	s_cbranch_execz .Lnbtbl_ld4
	v_lshl_add_u64 v[2:3], v[170:171], 2, s[0:1]
	global_load_dword v10, v[2:3], off
.Lnbtbl_ld4:
	s_or_b64 exec, exec, s[12:13]
	s_mov_b64 s[12:13], exec
	v_readlane_b32 s8, v252, 49
	v_readlane_b32 s9, v252, 50
	s_and_b64 s[8:9], s[12:13], s[8:9]
	s_mov_b64 exec, s[8:9]
	s_cbranch_execz .Lnbtbl_ld5
	v_lshl_add_u64 v[2:3], v[172:173], 2, s[0:1]
	global_load_dword v11, v[2:3], off
.Lnbtbl_ld5:
	s_or_b64 exec, exec, s[12:13]
	s_mov_b64 s[12:13], exec
	v_readlane_b32 s8, v252, 51
	v_readlane_b32 s9, v252, 52
	s_and_b64 s[8:9], s[12:13], s[8:9]
	s_mov_b64 exec, s[8:9]
	s_cbranch_execz .Lnbtbl_ld6
	v_lshl_add_u64 v[2:3], v[174:175], 2, s[0:1]
	global_load_dword v12, v[2:3], off
.Lnbtbl_ld6:
	s_or_b64 exec, exec, s[12:13]
	s_mov_b64 s[12:13], exec
	v_readlane_b32 s8, v252, 53
	v_readlane_b32 s9, v252, 54
	s_and_b64 s[8:9], s[12:13], s[8:9]
	s_mov_b64 exec, s[8:9]
	s_cbranch_execz .Lnbtbl_ld7
	v_lshl_add_u64 v[2:3], v[176:177], 2, s[0:1]
	global_load_dword v13, v[2:3], off
.Lnbtbl_ld7:
	s_or_b64 exec, exec, s[12:13]
	s_waitcnt vmcnt(0)
	s_mov_b64 s[12:13], exec
	v_readlane_b32 s8, v252, 38
	v_readlane_b32 s9, v252, 39
	s_and_b64 s[8:9], s[12:13], s[8:9]
	s_mov_b64 exec, s[8:9]
	v_mul_f32_e32 v6, 0x3fb8aa3b, v6
	s_mov_b64 exec, s[12:13]
	ds_write_b32 v147, v6 offset:17408
	s_mov_b64 s[12:13], exec
	v_readlane_b32 s8, v252, 41
	v_readlane_b32 s9, v252, 42
	s_and_b64 s[8:9], s[12:13], s[8:9]
	s_mov_b64 exec, s[8:9]
	v_mul_f32_e32 v7, 0x3fb8aa3b, v7
	s_mov_b64 exec, s[12:13]
	ds_write_b32 v147, v7 offset:17664
	s_mov_b64 s[12:13], exec
	v_readlane_b32 s8, v252, 43
	v_readlane_b32 s9, v252, 44
	s_and_b64 s[8:9], s[12:13], s[8:9]
	s_mov_b64 exec, s[8:9]
	v_mul_f32_e32 v8, 0x3fb8aa3b, v8
	s_mov_b64 exec, s[12:13]
	ds_write_b32 v147, v8 offset:17920
	s_mov_b64 s[12:13], exec
	v_readlane_b32 s8, v252, 45
	v_readlane_b32 s9, v252, 46
	s_and_b64 s[8:9], s[12:13], s[8:9]
	s_mov_b64 exec, s[8:9]
	v_mul_f32_e32 v9, 0x3fb8aa3b, v9
	s_mov_b64 exec, s[12:13]
	ds_write_b32 v147, v9 offset:18176
	s_mov_b64 s[12:13], exec
	v_readlane_b32 s8, v252, 47
	v_readlane_b32 s9, v252, 48
	s_and_b64 s[8:9], s[12:13], s[8:9]
	s_mov_b64 exec, s[8:9]
	v_mul_f32_e32 v10, 0x3fb8aa3b, v10
	s_mov_b64 exec, s[12:13]
	ds_write_b32 v147, v10 offset:18432
	s_mov_b64 s[12:13], exec
	v_readlane_b32 s8, v252, 49
	v_readlane_b32 s9, v252, 50
	s_and_b64 s[8:9], s[12:13], s[8:9]
	s_mov_b64 exec, s[8:9]
	v_mul_f32_e32 v11, 0x3fb8aa3b, v11
	s_mov_b64 exec, s[12:13]
	ds_write_b32 v147, v11 offset:18688
	s_mov_b64 s[12:13], exec
	v_readlane_b32 s8, v252, 51
	v_readlane_b32 s9, v252, 52
	s_and_b64 s[8:9], s[12:13], s[8:9]
	s_mov_b64 exec, s[8:9]
	v_mul_f32_e32 v12, 0x3fb8aa3b, v12
	s_mov_b64 exec, s[12:13]
	ds_write_b32 v147, v12 offset:18944
	s_mov_b64 s[12:13], exec
	v_readlane_b32 s8, v252, 53
	v_readlane_b32 s9, v252, 54
	s_and_b64 s[8:9], s[12:13], s[8:9]
	s_mov_b64 exec, s[8:9]
	v_mul_f32_e32 v13, 0x3fb8aa3b, v13
	s_mov_b64 exec, s[12:13]
	ds_write_b32 v147, v13 offset:19200
	s_lshl_b32 s0, s83, 5
	s_and_b32 s0, s0, 0x7fffff00
	s_add_i32 s0, s58, s0
	s_cmp_lt_i32 s0, 0x8000
	s_movk_i32 s1, 0xf800
	s_cselect_b32 s1, s1, 0x7fffe000
	s_cselect_b32 s21, 32, 0x80
	s_and_b32 s14, s1, s0
	s_sub_i32 s0, s0, s14
	s_ashr_i32 s15, s0, 7
	v_readlane_b32 s0, v252, 55
	s_add_i32 s15, s15, s0
	v_readlane_b32 s8, v252, 26
	s_lshl_b32 s0, s15, 1
	s_sub_i32 s12, s14, s8
	s_add_i32 s4, s21, -10
	s_add_i32 s21, s21, -8
	s_add_i32 s8, s0, -3
	s_add_i32 s1, s0, -4
	s_min_i32 s8, s8, s21
	s_min_i32 s4, s1, s4
	s_min_i32 s1, s1, s21
	s_add_i32 s8, s8, 7
	v_readlane_b32 s9, v252, 27
	s_cmp_lt_i32 s15, 2
	v_or_b32_e32 v1, s0, v169
	v_or_b32_e32 v3, s12, v208
	s_cselect_b32 s20, 0, s4
	s_cselect_b32 s8, 7, s8
	s_cselect_b32 s9, 0, s1
	s_add_i32 s13, s3, 12
	v_lshl_add_u32 v194, v1, 6, v3
	v_mov_b64_e32 v[4:5], s[96:97]
	v_mad_i64_i32 v[4:5], s[0:1], v194, s17, v[4:5]
	s_lshl_b32 s4, s13, 7
	v_lshl_add_u64 v[4:5], v[4:5], 0, s[4:5]
	v_lshl_add_u64 v[4:5], v[180:181], 1, v[4:5]
	global_load_dwordx4 v[66:69], v[4:5], off
	global_load_dwordx4 v[70:73], v[4:5], off offset:32
	global_load_dwordx4 v[74:77], v[4:5], off offset:64
	global_load_dwordx4 v[78:81], v[4:5], off offset:96
	s_sub_i32 s1, s9, s20
	s_max_i32 s26, s1, 0
	s_sub_i32 s0, s8, s20
	s_add_i32 s9, s26, s20
	s_min_i32 s0, s0, 9
	s_lshl_b32 s28, s9, 6
	s_sub_i32 s8, s0, s26
	s_add_i32 s0, s28, s12
	s_lshl_b32 s4, s13, 23
	s_cmp_gt_i32 s8, -1
	v_add_u32_e32 v2, s0, v226
	s_cselect_b64 s[0:1], -1, 0
	s_cmp_lt_i32 s8, 0
	v_lshl_add_u64 v[190:191], v[182:183], 0, s[4:5]
	s_cbranch_scc1 .LBB0_165
	v_ashrrev_i32_e32 v3, 31, v2
	v_lshlrev_b64 v[4:5], 8, v[2:3]
	v_lshl_add_u64 v[4:5], v[190:191], 0, v[4:5]
	v_add_co_u32_e32 v6, vcc, 0x1000, v4
	s_nop 1
	v_addc_co_u32_e32 v7, vcc, 0, v5, vcc
	global_load_dwordx4 v[82:85], v[4:5], off
	global_load_dwordx4 v[86:89], v[4:5], off offset:128
	global_load_dwordx4 v[94:97], v[4:5], off offset:2048
	global_load_dwordx4 v[90:93], v[4:5], off offset:2176
	global_load_dwordx4 v[102:105], v[6:7], off
	global_load_dwordx4 v[98:101], v[6:7], off offset:128
	global_load_dwordx4 v[110:113], v[6:7], off offset:2048
	global_load_dwordx4 v[106:109], v[6:7], off offset:2176

.LBB0_189:
	v_mov_b32_e32 v8, 0xf149f2ca
	v_mov_b32_e32 v9, 0xf149f2ca
	v_mov_b32_e32 v10, 0xf149f2ca
	s_lshl_b32 s3, s97, 2
	s_lshl_b32 s98, s97, 1
	s_or_b32 s12, s3, s26
	v_mov_b32_e32 v1, 0xf149f2ca
	s_and_saveexec_b64 s[14:15], s[38:39]
	s_cbranch_execz .LBB0_193
	v_lshlrev_b32_e32 v1, s98, v236
	v_sub_u32_e32 v2, 0, v1
	v_max_i32_e32 v2, v1, v2
	v_cmp_lt_u32_e32 vcc, 7, v2
	s_and_saveexec_b64 s[20:21], vcc
	s_cbranch_execz .LBB0_192
	v_cmp_lt_u32_e32 vcc, 14, v2
	s_movk_i32 s3, 0xa5
	s_nop 0
	v_cndmask_b32_e64 v3, 8, 9, vcc
	v_cmp_lt_u32_e32 vcc, 26, v2
	s_nop 1
	v_cndmask_b32_e64 v4, 0, 1, vcc
	v_cmp_lt_u32_e32 vcc, 49, v2
	s_nop 1
	v_addc_co_u32_e32 v3, vcc, v3, v4, vcc
	v_cmp_lt_u32_e32 vcc, s44, v2
	s_nop 1
	v_cndmask_b32_e64 v4, 0, 1, vcc
	v_cmp_lt_u32_e32 vcc, s3, v2
	s_movk_i32 s3, 0x130
	s_nop 0
	v_addc_co_u32_e32 v3, vcc, v3, v4, vcc
	v_cmp_lt_u32_e32 vcc, s3, v2
	s_movk_i32 s3, 0x22e
	s_nop 0
	v_cndmask_b32_e64 v4, 0, 1, vcc
	v_cmp_lt_u32_e32 vcc, s3, v2
	s_nop 1
	v_addc_co_u32_e32 v2, vcc, v3, v4, vcc
.LBB0_192:
	s_or_b64 exec, exec, s[20:21]
	v_cmp_lt_i32_e32 vcc, 0, v1
	s_nop 1
	v_cndmask_b32_e64 v1, 0, 16, vcc
	v_add_u32_e32 v1, v2, v1
	v_mov_b32_e32 v2, s12
	v_mad_u64_u32 v[2:3], s[8:9], v1, 12, v[2:3]
	v_mov_b32_e32 v3, v0
	v_lshl_add_u64 v[2:3], v[2:3], 2, s[70:71]
	global_load_dword v8, v[2:3], off
.LBB0_193:
	s_or_b64 exec, exec, s[14:15]
	v_mov_b32_e32 v1, 0xf149f2ca
	s_and_saveexec_b64 s[14:15], s[40:41]
	s_cbranch_execz .LBB0_197
	v_lshlrev_b32_e32 v1, s98, v235
	v_sub_u32_e32 v2, 0, v1
	v_max_i32_e32 v2, v1, v2
	v_cmp_lt_u32_e32 vcc, 7, v2
	s_and_saveexec_b64 s[20:21], vcc
	s_cbranch_execz .LBB0_196
	v_cmp_lt_u32_e32 vcc, 14, v2
	s_movk_i32 s3, 0xa5
	s_nop 0
	v_cndmask_b32_e64 v3, 8, 9, vcc
	v_cmp_lt_u32_e32 vcc, 26, v2
	s_nop 1
	v_cndmask_b32_e64 v4, 0, 1, vcc
	v_cmp_lt_u32_e32 vcc, 49, v2
	s_nop 1
	v_addc_co_u32_e32 v3, vcc, v3, v4, vcc
	v_cmp_lt_u32_e32 vcc, s44, v2
	s_nop 1
	v_cndmask_b32_e64 v4, 0, 1, vcc
	v_cmp_lt_u32_e32 vcc, s3, v2
	s_movk_i32 s3, 0x130
	s_nop 0
	v_addc_co_u32_e32 v3, vcc, v3, v4, vcc
	v_cmp_lt_u32_e32 vcc, s3, v2
	s_movk_i32 s3, 0x22e
	s_nop 0
	v_cndmask_b32_e64 v4, 0, 1, vcc
	v_cmp_lt_u32_e32 vcc, s3, v2
	s_nop 1
	v_addc_co_u32_e32 v2, vcc, v3, v4, vcc
.LBB0_196:
	s_or_b64 exec, exec, s[20:21]
	v_cmp_lt_i32_e32 vcc, 0, v1
	s_nop 1
	v_cndmask_b32_e64 v1, 0, 16, vcc
	v_add_u32_e32 v1, v2, v1
	v_mov_b32_e32 v2, s12
	v_mad_u64_u32 v[2:3], s[8:9], v1, 12, v[2:3]
	v_mov_b32_e32 v3, v0
	v_lshl_add_u64 v[2:3], v[2:3], 2, s[70:71]
	global_load_dword v9, v[2:3], off
.LBB0_197:
	s_or_b64 exec, exec, s[14:15]
	v_mov_b32_e32 v1, 0xf149f2ca
	s_and_saveexec_b64 s[14:15], s[42:43]
	s_cbranch_execz .LBB0_201
	v_lshlrev_b32_e32 v1, s98, v237
	v_sub_u32_e32 v2, 0, v1
	v_max_i32_e32 v2, v1, v2
	v_cmp_lt_u32_e32 vcc, 7, v2
	s_and_saveexec_b64 s[20:21], vcc
	s_cbranch_execz .LBB0_200
	v_cmp_lt_u32_e32 vcc, 14, v2
	s_movk_i32 s3, 0xa5
	s_nop 0
	v_cndmask_b32_e64 v3, 8, 9, vcc
	v_cmp_lt_u32_e32 vcc, 26, v2
	s_nop 1
	v_cndmask_b32_e64 v4, 0, 1, vcc
	v_cmp_lt_u32_e32 vcc, 49, v2
	s_nop 1
	v_addc_co_u32_e32 v3, vcc, v3, v4, vcc
	v_cmp_lt_u32_e32 vcc, s44, v2
	s_nop 1
	v_cndmask_b32_e64 v4, 0, 1, vcc
	v_cmp_lt_u32_e32 vcc, s3, v2
	s_movk_i32 s3, 0x130
	s_nop 0
	v_addc_co_u32_e32 v3, vcc, v3, v4, vcc
	v_cmp_lt_u32_e32 vcc, s3, v2
	s_movk_i32 s3, 0x22e
	s_nop 0
	v_cndmask_b32_e64 v4, 0, 1, vcc
	v_cmp_lt_u32_e32 vcc, s3, v2
	s_nop 1
	v_addc_co_u32_e32 v2, vcc, v3, v4, vcc
.LBB0_200:
	s_or_b64 exec, exec, s[20:21]
	v_cmp_lt_i32_e32 vcc, 0, v1
	s_nop 1
	v_cndmask_b32_e64 v1, 0, 16, vcc
	v_add_u32_e32 v1, v2, v1
	v_mov_b32_e32 v2, s12
	v_mad_u64_u32 v[2:3], s[8:9], v1, 12, v[2:3]
	v_mov_b32_e32 v3, v0
	v_lshl_add_u64 v[2:3], v[2:3], 2, s[70:71]
	global_load_dword v10, v[2:3], off
.LBB0_201:
	s_or_b64 exec, exec, s[14:15]
	s_waitcnt vmcnt(0)
	s_and_saveexec_b64 s[14:15], s[38:39]
	v_mul_f32_e32 v8, 0x3fb8aa3b, v8
	s_or_b64 exec, exec, s[14:15]
	ds_write_b32 v147, v8 offset:17408
	s_and_saveexec_b64 s[14:15], s[40:41]
	v_mul_f32_e32 v9, 0x3fb8aa3b, v9
	s_or_b64 exec, exec, s[14:15]
	ds_write_b32 v147, v9 offset:17664
	s_and_saveexec_b64 s[14:15], s[42:43]
	v_mul_f32_e32 v10, 0x3fb8aa3b, v10
	s_or_b64 exec, exec, s[14:15]
	ds_write_b32 v147, v10 offset:17920
	s_lshl_b32 s3, 1, s98
	s_ashr_i32 s4, s3, 31
	s_add_i32 s3, s3, s4
	s_xor_b32 s3, s3, s4
	v_cvt_f32_u32_e32 v2, s3
	s_sub_i32 s14, 0, s3
	s_ashr_i32 s8, s96, 31
	v_rcp_iflag_f32_e32 v1, v2
	s_add_i32 s13, s96, s8
	s_xor_b32 s13, s13, s8
	s_lshr_b32 s99, s29, s98
	v_mul_f32_e32 v1, 0x4f7ffffe, v1
	v_cvt_u32_f32_e32 v1, v1
	s_mov_b32 s9, 0
	v_readfirstlane_b32 s15, v1
	s_mul_i32 s14, s14, s15
	s_mul_hi_u32 s14, s15, s14
	s_add_i32 s15, s15, s14
	s_mul_hi_u32 s14, s13, s15
	s_mul_i32 s20, s14, s3
	s_sub_i32 s13, s13, s20
	s_add_i32 s15, s14, 1
	s_sub_i32 s20, s13, s3
	s_cmp_ge_u32 s13, s3
	s_cselect_b32 s14, s15, s14
	s_cselect_b32 s13, s20, s13
	s_add_i32 s15, s14, 1
	s_cmp_ge_u32 s13, s3
	s_cselect_b32 s3, s15, s14
	s_xor_b32 s4, s8, s4
	s_xor_b32 s3, s3, s4
	s_mov_b32 s13, s5
	s_sub_i32 s3, s3, s4
	s_lshl_b32 s4, s12, 6
	s_sub_i32 s8, s99, 64
	s_lshl_b64 s[12:13], s[12:13], 23
	v_lshl_add_u64 v[194:195], v[182:183], 0, s[12:13]
	s_cmp_lg_u32 s97, 2
	v_sub_co_u32_e64 v1, s[12:13], s97, 1
	v_lshl_add_u64 v[192:193], s[4:5], 1, v[184:185]
	s_cselect_b64 s[46:47], -1, 0
	v_readfirstlane_b32 s4, v1
	s_mov_b64 s[20:21], -1
	s_xor_b64 s[14:15], s[12:13], -1
	v_add_u32_e32 v244, s3, v243
	s_branch .LBB0_203
